# ff2 GEMM K-loop: 3-deep prefetch ring, 6 k-tiles per loop iteration
# speedup vs baseline: 1.0874x; 1.0098x over previous
; #define MFMA(a, b, c) __builtin_amdgcn_mfma_f32_32x32x16_bf16((a), (b), (c), 0, 0, 0)
; template <class Epi, class ColV>
; DI void gemm_tile(const bf16_t* __restrict__ A, int lda, const bf16_t* __restrict__ Bt, int ldb, int K, int m0, int n0, unsigned char* smem, Epi epi, ColV colv, const bf16_t* __restrict__ HYT = nullptr) {
;     ...
;     auto gload = [&](u32x4 (&r)[8], int kt) {
; #pragma unroll
;         for (int i = 0; i < 4; ++i) { int id = tid + 256 * i, row = id >> 3, kc = id & 7;
;             if (HYT && kt >= 12) r[i] = *(const u32x4*)(HYT + (size_t)((kt - 12) * 64 + (id >> 4)) * NT + m0 + (id & 15) * 8);
;             else r[i] = *(const u32x4*)(A + (size_t)(m0 + row) * lda + kt * 64 + kc * 8);
;             r[4 + i] = *(const u32x4*)(Bt + (size_t)(n0 + row) * ldb + kt * 64 + kc * 8); }
;     };
;     auto sstore = [&](const u32x4 (&r)[8], int buf, int kt) {
; #pragma unroll
;         for (int i = 0; i < 4; ++i) { int id = tid + 256 * i, row = id >> 3, kc = id & 7;
;             if (HYT && kt >= 12) { const int kk = id >> 4, rr = (id & 15) * 8; bf16_t* d = As + (buf * 128 + rr) * LS + kk; const bf16x8 v = __builtin_bit_cast(bf16x8, r[i]);
; #pragma unroll
;                 for (int e = 0; e < 8; ++e) d[e * LS] = (bf16_t)v[e]; }
;             else *(u32x4*)(As + (buf * 128 + row) * LS + kc * 8) = r[i];
;             *(u32x4*)(Bs + (buf * 128 + row) * LS + kc * 8) = r[4 + i]; }
;     };
;     auto step = [&](int kt, u32x4 (&ldset)[8], const u32x4 (&stset)[8]) {
;         const int buf = kt & 1;
;         if (kt + 2 < nk) gload(ldset, kt + 2);
;         const bf16_t* Ab = As + (buf * 128 + 64 * wr + li) * LS + 8 * lh;
;         const bf16_t* Bb = Bs + (buf * 128 + 64 * wc + li) * LS + 8 * lh;
;         bf16x8 fa[2][2], fb[2][2], ga[2][2], gb[2][2];
; #pragma unroll
;         for (int k2 = 0; k2 < 2; ++k2) { fa[k2][0] = ld8(Ab + 16 * k2); fa[k2][1] = ld8(Ab + 32 * LS + 16 * k2); fb[k2][0] = ld8(Bb + 16 * k2); fb[k2][1] = ld8(Bb + 32 * LS + 16 * k2); }
;         __builtin_amdgcn_sched_barrier(0);
; #pragma unroll
;         for (int k2 = 0; k2 < 2; ++k2) {
;             acc[0][0] = MFMA(fa[k2][0], fb[k2][0], acc[0][0]); acc[0][1] = MFMA(fa[k2][0], fb[k2][1], acc[0][1]);
;             acc[1][0] = MFMA(fa[k2][1], fb[k2][0], acc[1][0]); acc[1][1] = MFMA(fa[k2][1], fb[k2][1], acc[1][1]);
;         }
; #pragma unroll
.LBB0_40:
	s_cmp_lt_u32 s41, 62
	s_cselect_b64 s[18:19], -1, 0
	s_cmp_gt_u32 s41, 61
	s_cselect_b64 s[12:13], -1, 0
	s_and_b64 vcc, exec, s[12:13]
	v_lshl_add_u64 v[164:165], v[144:145], 0, v[2:3]
	v_lshl_add_u64 v[162:163], v[142:143], 0, v[2:3]
	v_lshl_add_u64 v[160:161], v[140:141], 0, v[2:3]
	v_lshl_add_u64 v[158:159], v[138:139], 0, v[2:3]
	v_lshl_add_u64 v[156:157], v[136:137], 0, v[2:3]
	v_lshl_add_u64 v[154:155], v[134:135], 0, v[2:3]
	v_lshl_add_u64 v[152:153], v[132:133], 0, v[2:3]
	v_lshl_add_u64 v[146:147], v[0:1], 0, v[2:3]
	s_mov_b32 s100, 0x48ca000
	s_mov_b32 s101, 0
	v_lshl_add_u64 v[164:165], v[164:165], 0, s[100:101]
	v_lshl_add_u64 v[160:161], v[160:161], 0, s[100:101]
	v_lshl_add_u64 v[156:157], v[156:157], 0, s[100:101]
	v_lshl_add_u64 v[152:153], v[152:153], 0, s[100:101]
	s_mov_b32 s100, 0xe80000
	s_mov_b32 s101, 0
	v_lshl_add_u64 v[162:163], v[162:163], 0, s[100:101]
	v_lshl_add_u64 v[158:159], v[158:159], 0, s[100:101]
	v_lshl_add_u64 v[154:155], v[154:155], 0, s[100:101]
	v_lshl_add_u64 v[146:147], v[146:147], 0, s[100:101]
	global_load_dwordx4 v[132:135], v[164:165], off offset:256
	global_load_dwordx4 v[136:139], v[162:163], off offset:256
	global_load_dwordx4 v[140:143], v[160:161], off offset:256
	global_load_dwordx4 v[198:201], v[158:159], off offset:256
	global_load_dwordx4 v[226:229], v[156:157], off offset:256
	global_load_dwordx4 v[230:233], v[154:155], off offset:256
	global_load_dwordx4 v[242:245], v[152:153], off offset:256
	global_load_dwordx4 v[246:249], v[146:147], off offset:256
	s_mov_b32 s100, 0x300
	s_mov_b32 s101, 0
	s_mov_b32 s41, 10
.Lg3_phase11:
	global_load_dwordx4 v[68:71], v[164:165], off offset:384
	global_load_dwordx4 v[72:75], v[162:163], off offset:384
	global_load_dwordx4 v[76:79], v[160:161], off offset:384
	global_load_dwordx4 v[80:83], v[158:159], off offset:384
	global_load_dwordx4 v[84:87], v[156:157], off offset:384
	global_load_dwordx4 v[92:95], v[154:155], off offset:384
	global_load_dwordx4 v[104:107], v[152:153], off offset:384
	global_load_dwordx4 v[112:115], v[146:147], off offset:384
	ds_read_b128 v[174:177], v194
	ds_read_b128 v[178:181], v194 offset:32
	ds_read_b128 v[202:205], v194 offset:4608
	ds_read_b128 v[206:209], v194 offset:4640
	ds_read_b128 v[210:213], v195 offset:36864
	ds_read_b128 v[214:217], v195 offset:36896
	ds_read_b128 v[218:221], v195 offset:41472
	ds_read_b128 v[222:225], v195 offset:41504
	s_waitcnt lgkmcnt(3)
	v_mfma_f32_32x32x16_bf16 v[52:67], v[174:177], v[210:213], v[52:67]
	s_waitcnt lgkmcnt(1)
	v_mfma_f32_32x32x16_bf16 v[36:51], v[174:177], v[218:221], v[36:51]
	v_mfma_f32_32x32x16_bf16 v[4:19], v[202:205], v[218:221], v[4:19]
	s_waitcnt lgkmcnt(0)
	v_mfma_f32_32x32x16_bf16 v[36:51], v[178:181], v[222:225], v[36:51]
	v_mfma_f32_32x32x16_bf16 v[4:19], v[206:209], v[222:225], v[4:19]
	ds_read_b128 v[222:225], v195 offset:41568
	ds_read_b128 v[174:177], v194 offset:4672
	v_mfma_f32_32x32x16_bf16 v[20:35], v[202:205], v[210:213], v[20:35]
	ds_read_b128 v[210:213], v194 offset:4704
	ds_read_b128 v[202:205], v194 offset:64
	v_mfma_f32_32x32x16_bf16 v[52:67], v[178:181], v[214:217], v[52:67]
	ds_read_b128 v[218:221], v195 offset:36960
	ds_read_b128 v[178:181], v195 offset:41536
	v_mfma_f32_32x32x16_bf16 v[20:35], v[206:209], v[214:217], v[20:35]
	ds_read_b128 v[214:217], v195 offset:36928
	ds_read_b128 v[206:209], v194 offset:96
	s_waitcnt lgkmcnt(1)
	v_mfma_f32_32x32x16_bf16 v[52:67], v[202:205], v[214:217], v[52:67]
	s_waitcnt vmcnt(23)
	ds_write_b128 v190, v[88:91] offset:18432
	v_mfma_f32_32x32x16_bf16 v[36:51], v[202:205], v[178:181], v[36:51]
	s_waitcnt vmcnt(22)
	ds_write_b128 v190, v[96:99] offset:55296
	v_mfma_f32_32x32x16_bf16 v[20:35], v[174:177], v[214:217], v[20:35]
	s_waitcnt vmcnt(21)
	ds_write_b128 v191, v[100:103] offset:18432
	v_mfma_f32_32x32x16_bf16 v[4:19], v[174:177], v[178:181], v[4:19]
	s_waitcnt vmcnt(20)
	ds_write_b128 v191, v[108:111] offset:55296
	s_waitcnt lgkmcnt(4)
	v_mfma_f32_32x32x16_bf16 v[52:67], v[206:209], v[218:221], v[52:67]
	s_waitcnt vmcnt(19)
	ds_write_b128 v192, v[116:119] offset:18432
	v_mfma_f32_32x32x16_bf16 v[36:51], v[206:209], v[222:225], v[36:51]
	s_waitcnt vmcnt(18)
	ds_write_b128 v192, v[120:123] offset:55296
	v_mfma_f32_32x32x16_bf16 v[20:35], v[210:213], v[218:221], v[20:35]
	s_waitcnt vmcnt(17)
	ds_write_b128 v193, v[124:127] offset:18432
	v_mfma_f32_32x32x16_bf16 v[4:19], v[210:213], v[222:225], v[4:19]
	s_waitcnt vmcnt(16)
	ds_write_b128 v193, v[128:131] offset:55296
	s_waitcnt lgkmcnt(0)
	s_barrier
; #define MFMA(a, b, c) __builtin_amdgcn_mfma_f32_32x32x16_bf16((a), (b), (c), 0, 0, 0)
; template <class Epi, class ColV>
; DI void gemm_tile(const bf16_t* __restrict__ A, int lda, const bf16_t* __restrict__ Bt, int ldb, int K, int m0, int n0, unsigned char* smem, Epi epi, ColV colv, const bf16_t* __restrict__ HYT = nullptr) {
;     ...
;     auto step = [&](int kt, u32x4 (&ldset)[8], const u32x4 (&stset)[8]) {
;         const int buf = kt & 1;
;         if (kt + 2 < nk) gload(ldset, kt + 2);
;         const bf16_t* Ab = As + (buf * 128 + 64 * wr + li) * LS + 8 * lh;
;         const bf16_t* Bb = Bs + (buf * 128 + 64 * wc + li) * LS + 8 * lh;
;         bf16x8 fa[2][2], fb[2][2], ga[2][2], gb[2][2];
; #pragma unroll
;         for (int k2 = 0; k2 < 2; ++k2) { fa[k2][0] = ld8(Ab + 16 * k2); fa[k2][1] = ld8(Ab + 32 * LS + 16 * k2); fb[k2][0] = ld8(Bb + 16 * k2); fb[k2][1] = ld8(Bb + 32 * LS + 16 * k2); }
;         __builtin_amdgcn_sched_barrier(0);
; #pragma unroll
;         for (int k2 = 0; k2 < 2; ++k2) {
;             acc[0][0] = MFMA(fa[k2][0], fb[k2][0], acc[0][0]); acc[0][1] = MFMA(fa[k2][0], fb[k2][1], acc[0][1]);
;             acc[1][0] = MFMA(fa[k2][1], fb[k2][0], acc[1][0]); acc[1][1] = MFMA(fa[k2][1], fb[k2][1], acc[1][1]);
;         }
; #pragma unroll
;         for (int k2 = 0; k2 < 2; ++k2) { const int ks = 2 + k2; ga[k2][0] = ld8(Ab + 16 * ks); ga[k2][1] = ld8(Ab + 32 * LS + 16 * ks); gb[k2][0] = ld8(Bb + 16 * ks); gb[k2][1] = ld8(Bb + 32 * LS + 16 * ks); }
; #pragma unroll
;         for (int k2 = 0; k2 < 2; ++k2) {
;             acc[0][0] = MFMA(ga[k2][0], gb[k2][0], acc[0][0]); acc[0][1] = MFMA(ga[k2][0], gb[k2][1], acc[0][1]);
;             acc[1][0] = MFMA(ga[k2][1], gb[k2][0], acc[1][0]); acc[1][1] = MFMA(ga[k2][1], gb[k2][1], acc[1][1]);
;         }
;         if (kt + 1 < nk) sstore(stset, buf ^ 1, kt + 1);
; #pragma unroll
;         for (int i = 0; i < 8; ++i) { __builtin_amdgcn_sched_group_barrier(0x008, 1, 0); __builtin_amdgcn_sched_group_barrier(0x100, 1, 0); }
; #pragma unroll
;         for (int i = 0; i < 8; ++i) { __builtin_amdgcn_sched_group_barrier(0x008, 1, 0); __builtin_amdgcn_sched_group_barrier(0x200, 1, 0); }
;         __builtin_amdgcn_sched_barrier(0);
;         __syncthreads();
;     };
	global_load_dwordx4 v[88:91], v[164:165], off offset:512
	global_load_dwordx4 v[96:99], v[162:163], off offset:512
	global_load_dwordx4 v[100:103], v[160:161], off offset:512
	global_load_dwordx4 v[108:111], v[158:159], off offset:512
	global_load_dwordx4 v[116:119], v[156:157], off offset:512
	global_load_dwordx4 v[120:123], v[154:155], off offset:512
	global_load_dwordx4 v[124:127], v[152:153], off offset:512
	global_load_dwordx4 v[128:131], v[146:147], off offset:512
	ds_read_b128 v[174:177], v196
	ds_read_b128 v[178:181], v196 offset:32
	ds_read_b128 v[202:205], v196 offset:4608
	ds_read_b128 v[206:209], v196 offset:4640
	ds_read_b128 v[210:213], v197 offset:36864
	ds_read_b128 v[214:217], v197 offset:36896
	ds_read_b128 v[218:221], v197 offset:41472
	ds_read_b128 v[222:225], v197 offset:41504
	s_waitcnt lgkmcnt(3)
	v_mfma_f32_32x32x16_bf16 v[52:67], v[174:177], v[210:213], v[52:67]
	s_waitcnt lgkmcnt(1)
	v_mfma_f32_32x32x16_bf16 v[36:51], v[174:177], v[218:221], v[36:51]
	v_mfma_f32_32x32x16_bf16 v[4:19], v[202:205], v[218:221], v[4:19]
	s_waitcnt lgkmcnt(0)
	v_mfma_f32_32x32x16_bf16 v[36:51], v[178:181], v[222:225], v[36:51]
	v_mfma_f32_32x32x16_bf16 v[4:19], v[206:209], v[222:225], v[4:19]
	ds_read_b128 v[222:225], v197 offset:41568
	ds_read_b128 v[174:177], v196 offset:4672
	v_mfma_f32_32x32x16_bf16 v[20:35], v[202:205], v[210:213], v[20:35]
	ds_read_b128 v[210:213], v196 offset:4704
	ds_read_b128 v[202:205], v196 offset:64
	v_mfma_f32_32x32x16_bf16 v[52:67], v[178:181], v[214:217], v[52:67]
	ds_read_b128 v[218:221], v197 offset:36960
	ds_read_b128 v[178:181], v197 offset:41536
	v_mfma_f32_32x32x16_bf16 v[20:35], v[206:209], v[214:217], v[20:35]
	ds_read_b128 v[214:217], v197 offset:36928
	ds_read_b128 v[206:209], v196 offset:96
	s_waitcnt lgkmcnt(1)
	v_mfma_f32_32x32x16_bf16 v[52:67], v[202:205], v[214:217], v[52:67]
	s_waitcnt vmcnt(23)
	ds_write_b128 v190, v[132:135]
	v_mfma_f32_32x32x16_bf16 v[36:51], v[202:205], v[178:181], v[36:51]
	s_waitcnt vmcnt(22)
	ds_write_b128 v190, v[136:139] offset:36864
	v_mfma_f32_32x32x16_bf16 v[20:35], v[174:177], v[214:217], v[20:35]
	s_waitcnt vmcnt(21)
	ds_write_b128 v191, v[140:143]
	v_mfma_f32_32x32x16_bf16 v[4:19], v[174:177], v[178:181], v[4:19]
	s_waitcnt vmcnt(20)
	ds_write_b128 v191, v[198:201] offset:36864
	s_waitcnt lgkmcnt(4)
	v_mfma_f32_32x32x16_bf16 v[52:67], v[206:209], v[218:221], v[52:67]
	s_waitcnt vmcnt(19)
	ds_write_b128 v192, v[226:229]
	v_mfma_f32_32x32x16_bf16 v[36:51], v[206:209], v[222:225], v[36:51]
	s_waitcnt vmcnt(18)
	ds_write_b128 v192, v[230:233] offset:36864
	v_mfma_f32_32x32x16_bf16 v[20:35], v[210:213], v[218:221], v[20:35]
	s_waitcnt vmcnt(17)
	ds_write_b128 v193, v[242:245]
	v_mfma_f32_32x32x16_bf16 v[4:19], v[210:213], v[222:225], v[4:19]
	s_waitcnt vmcnt(16)
	ds_write_b128 v193, v[246:249] offset:36864
	s_waitcnt lgkmcnt(0)
	s_barrier
	global_load_dwordx4 v[132:135], v[164:165], off offset:640
	global_load_dwordx4 v[136:139], v[162:163], off offset:640
	global_load_dwordx4 v[140:143], v[160:161], off offset:640
	global_load_dwordx4 v[198:201], v[158:159], off offset:640
	global_load_dwordx4 v[226:229], v[156:157], off offset:640
	global_load_dwordx4 v[230:233], v[154:155], off offset:640
	global_load_dwordx4 v[242:245], v[152:153], off offset:640
	global_load_dwordx4 v[246:249], v[146:147], off offset:640
	ds_read_b128 v[174:177], v194
	ds_read_b128 v[178:181], v194 offset:32
	ds_read_b128 v[202:205], v194 offset:4608
	ds_read_b128 v[206:209], v194 offset:4640
	ds_read_b128 v[210:213], v195 offset:36864
	ds_read_b128 v[214:217], v195 offset:36896
	ds_read_b128 v[218:221], v195 offset:41472
	ds_read_b128 v[222:225], v195 offset:41504
	s_waitcnt lgkmcnt(3)
	v_mfma_f32_32x32x16_bf16 v[52:67], v[174:177], v[210:213], v[52:67]
	s_waitcnt lgkmcnt(1)
	v_mfma_f32_32x32x16_bf16 v[36:51], v[174:177], v[218:221], v[36:51]
	v_mfma_f32_32x32x16_bf16 v[4:19], v[202:205], v[218:221], v[4:19]
	s_waitcnt lgkmcnt(0)
	v_mfma_f32_32x32x16_bf16 v[36:51], v[178:181], v[222:225], v[36:51]
	v_mfma_f32_32x32x16_bf16 v[4:19], v[206:209], v[222:225], v[4:19]
	ds_read_b128 v[222:225], v195 offset:41568
	ds_read_b128 v[174:177], v194 offset:4672
	v_mfma_f32_32x32x16_bf16 v[20:35], v[202:205], v[210:213], v[20:35]
	ds_read_b128 v[210:213], v194 offset:4704
	ds_read_b128 v[202:205], v194 offset:64
	v_mfma_f32_32x32x16_bf16 v[52:67], v[178:181], v[214:217], v[52:67]
	ds_read_b128 v[218:221], v195 offset:36960
	ds_read_b128 v[178:181], v195 offset:41536
	v_mfma_f32_32x32x16_bf16 v[20:35], v[206:209], v[214:217], v[20:35]
	ds_read_b128 v[214:217], v195 offset:36928
	ds_read_b128 v[206:209], v194 offset:96
	s_waitcnt lgkmcnt(1)
	v_mfma_f32_32x32x16_bf16 v[52:67], v[202:205], v[214:217], v[52:67]
	s_waitcnt vmcnt(23)
	ds_write_b128 v190, v[68:71] offset:18432
	v_mfma_f32_32x32x16_bf16 v[36:51], v[202:205], v[178:181], v[36:51]
	s_waitcnt vmcnt(22)
	ds_write_b128 v190, v[72:75] offset:55296
	v_mfma_f32_32x32x16_bf16 v[20:35], v[174:177], v[214:217], v[20:35]
	s_waitcnt vmcnt(21)
	ds_write_b128 v191, v[76:79] offset:18432
	v_mfma_f32_32x32x16_bf16 v[4:19], v[174:177], v[178:181], v[4:19]
	s_waitcnt vmcnt(20)
	ds_write_b128 v191, v[80:83] offset:55296
	s_waitcnt lgkmcnt(4)
	v_mfma_f32_32x32x16_bf16 v[52:67], v[206:209], v[218:221], v[52:67]
	s_waitcnt vmcnt(19)
	ds_write_b128 v192, v[84:87] offset:18432
	v_mfma_f32_32x32x16_bf16 v[36:51], v[206:209], v[222:225], v[36:51]
	s_waitcnt vmcnt(18)
	ds_write_b128 v192, v[92:95] offset:55296
	v_mfma_f32_32x32x16_bf16 v[20:35], v[210:213], v[218:221], v[20:35]
	s_waitcnt vmcnt(17)
	ds_write_b128 v193, v[104:107] offset:18432
	v_mfma_f32_32x32x16_bf16 v[4:19], v[210:213], v[222:225], v[4:19]
	s_waitcnt vmcnt(16)
	ds_write_b128 v193, v[112:115] offset:55296
	s_waitcnt lgkmcnt(0)
	s_barrier
; #define MFMA(a, b, c) __builtin_amdgcn_mfma_f32_32x32x16_bf16((a), (b), (c), 0, 0, 0)
; template <class Epi, class ColV>
; DI void gemm_tile(const bf16_t* __restrict__ A, int lda, const bf16_t* __restrict__ Bt, int ldb, int K, int m0, int n0, unsigned char* smem, Epi epi, ColV colv, const bf16_t* __restrict__ HYT = nullptr) {
;     ...
;     auto step = [&](int kt, u32x4 (&ldset)[8], const u32x4 (&stset)[8]) {
;         const int buf = kt & 1;
;         if (kt + 2 < nk) gload(ldset, kt + 2);
;         const bf16_t* Ab = As + (buf * 128 + 64 * wr + li) * LS + 8 * lh;
;         const bf16_t* Bb = Bs + (buf * 128 + 64 * wc + li) * LS + 8 * lh;
;         bf16x8 fa[2][2], fb[2][2], ga[2][2], gb[2][2];
; #pragma unroll
;         for (int k2 = 0; k2 < 2; ++k2) { fa[k2][0] = ld8(Ab + 16 * k2); fa[k2][1] = ld8(Ab + 32 * LS + 16 * k2); fb[k2][0] = ld8(Bb + 16 * k2); fb[k2][1] = ld8(Bb + 32 * LS + 16 * k2); }
;         __builtin_amdgcn_sched_barrier(0);
; #pragma unroll
;         for (int k2 = 0; k2 < 2; ++k2) {
;             acc[0][0] = MFMA(fa[k2][0], fb[k2][0], acc[0][0]); acc[0][1] = MFMA(fa[k2][0], fb[k2][1], acc[0][1]);
;             acc[1][0] = MFMA(fa[k2][1], fb[k2][0], acc[1][0]); acc[1][1] = MFMA(fa[k2][1], fb[k2][1], acc[1][1]);
;         }
; #pragma unroll
;         for (int k2 = 0; k2 < 2; ++k2) { const int ks = 2 + k2; ga[k2][0] = ld8(Ab + 16 * ks); ga[k2][1] = ld8(Ab + 32 * LS + 16 * ks); gb[k2][0] = ld8(Bb + 16 * ks); gb[k2][1] = ld8(Bb + 32 * LS + 16 * ks); }
; #pragma unroll
;         for (int k2 = 0; k2 < 2; ++k2) {
;             acc[0][0] = MFMA(ga[k2][0], gb[k2][0], acc[0][0]); acc[0][1] = MFMA(ga[k2][0], gb[k2][1], acc[0][1]);
;             acc[1][0] = MFMA(ga[k2][1], gb[k2][0], acc[1][0]); acc[1][1] = MFMA(ga[k2][1], gb[k2][1], acc[1][1]);
;         }
;         if (kt + 1 < nk) sstore(stset, buf ^ 1, kt + 1);
; #pragma unroll
;         for (int i = 0; i < 8; ++i) { __builtin_amdgcn_sched_group_barrier(0x008, 1, 0); __builtin_amdgcn_sched_group_barrier(0x100, 1, 0); }
; #pragma unroll
;         for (int i = 0; i < 8; ++i) { __builtin_amdgcn_sched_group_barrier(0x008, 1, 0); __builtin_amdgcn_sched_group_barrier(0x200, 1, 0); }
;         __builtin_amdgcn_sched_barrier(0);
;         __syncthreads();
;     };
	global_load_dwordx4 v[68:71], v[164:165], off offset:768
	global_load_dwordx4 v[72:75], v[162:163], off offset:768
	global_load_dwordx4 v[76:79], v[160:161], off offset:768
	global_load_dwordx4 v[80:83], v[158:159], off offset:768
	global_load_dwordx4 v[84:87], v[156:157], off offset:768
	global_load_dwordx4 v[92:95], v[154:155], off offset:768
	global_load_dwordx4 v[104:107], v[152:153], off offset:768
	global_load_dwordx4 v[112:115], v[146:147], off offset:768
	ds_read_b128 v[174:177], v196
	ds_read_b128 v[178:181], v196 offset:32
	ds_read_b128 v[202:205], v196 offset:4608
	ds_read_b128 v[206:209], v196 offset:4640
	ds_read_b128 v[210:213], v197 offset:36864
	ds_read_b128 v[214:217], v197 offset:36896
	ds_read_b128 v[218:221], v197 offset:41472
	ds_read_b128 v[222:225], v197 offset:41504
	s_waitcnt lgkmcnt(3)
	v_mfma_f32_32x32x16_bf16 v[52:67], v[174:177], v[210:213], v[52:67]
	s_waitcnt lgkmcnt(1)
	v_mfma_f32_32x32x16_bf16 v[36:51], v[174:177], v[218:221], v[36:51]
	v_mfma_f32_32x32x16_bf16 v[4:19], v[202:205], v[218:221], v[4:19]
	s_waitcnt lgkmcnt(0)
	v_mfma_f32_32x32x16_bf16 v[36:51], v[178:181], v[222:225], v[36:51]
	v_mfma_f32_32x32x16_bf16 v[4:19], v[206:209], v[222:225], v[4:19]
	ds_read_b128 v[222:225], v197 offset:41568
	ds_read_b128 v[174:177], v196 offset:4672
	v_mfma_f32_32x32x16_bf16 v[20:35], v[202:205], v[210:213], v[20:35]
	ds_read_b128 v[210:213], v196 offset:4704
	ds_read_b128 v[202:205], v196 offset:64
	v_mfma_f32_32x32x16_bf16 v[52:67], v[178:181], v[214:217], v[52:67]
	ds_read_b128 v[218:221], v197 offset:36960
	ds_read_b128 v[178:181], v197 offset:41536
	v_mfma_f32_32x32x16_bf16 v[20:35], v[206:209], v[214:217], v[20:35]
	ds_read_b128 v[214:217], v197 offset:36928
	ds_read_b128 v[206:209], v196 offset:96
	s_waitcnt lgkmcnt(1)
	v_mfma_f32_32x32x16_bf16 v[52:67], v[202:205], v[214:217], v[52:67]
	s_waitcnt vmcnt(23)
	ds_write_b128 v190, v[88:91]
	v_mfma_f32_32x32x16_bf16 v[36:51], v[202:205], v[178:181], v[36:51]
	s_waitcnt vmcnt(22)
	ds_write_b128 v190, v[96:99] offset:36864
	v_mfma_f32_32x32x16_bf16 v[20:35], v[174:177], v[214:217], v[20:35]
	s_waitcnt vmcnt(21)
	ds_write_b128 v191, v[100:103]
	v_mfma_f32_32x32x16_bf16 v[4:19], v[174:177], v[178:181], v[4:19]
	s_waitcnt vmcnt(20)
	ds_write_b128 v191, v[108:111] offset:36864
	s_waitcnt lgkmcnt(4)
	v_mfma_f32_32x32x16_bf16 v[52:67], v[206:209], v[218:221], v[52:67]
	s_waitcnt vmcnt(19)
	ds_write_b128 v192, v[116:119]
	v_mfma_f32_32x32x16_bf16 v[36:51], v[206:209], v[222:225], v[36:51]
	s_waitcnt vmcnt(18)
	ds_write_b128 v192, v[120:123] offset:36864
	v_mfma_f32_32x32x16_bf16 v[20:35], v[210:213], v[218:221], v[20:35]
	s_waitcnt vmcnt(17)
	ds_write_b128 v193, v[124:127]
	v_mfma_f32_32x32x16_bf16 v[4:19], v[210:213], v[222:225], v[4:19]
	s_waitcnt vmcnt(16)
	ds_write_b128 v193, v[128:131] offset:36864
	s_waitcnt lgkmcnt(0)
	s_barrier
	global_load_dwordx4 v[88:91], v[164:165], off offset:896
	global_load_dwordx4 v[96:99], v[162:163], off offset:896
	global_load_dwordx4 v[100:103], v[160:161], off offset:896
	global_load_dwordx4 v[108:111], v[158:159], off offset:896
	global_load_dwordx4 v[116:119], v[156:157], off offset:896
	global_load_dwordx4 v[120:123], v[154:155], off offset:896
	global_load_dwordx4 v[124:127], v[152:153], off offset:896
	global_load_dwordx4 v[128:131], v[146:147], off offset:896
	ds_read_b128 v[174:177], v194
	ds_read_b128 v[178:181], v194 offset:32
	ds_read_b128 v[202:205], v194 offset:4608
	ds_read_b128 v[206:209], v194 offset:4640
	ds_read_b128 v[210:213], v195 offset:36864
	ds_read_b128 v[214:217], v195 offset:36896
	ds_read_b128 v[218:221], v195 offset:41472
	ds_read_b128 v[222:225], v195 offset:41504
	s_waitcnt lgkmcnt(3)
	v_mfma_f32_32x32x16_bf16 v[52:67], v[174:177], v[210:213], v[52:67]
	s_waitcnt lgkmcnt(1)
	v_mfma_f32_32x32x16_bf16 v[36:51], v[174:177], v[218:221], v[36:51]
	v_mfma_f32_32x32x16_bf16 v[4:19], v[202:205], v[218:221], v[4:19]
	s_waitcnt lgkmcnt(0)
	v_mfma_f32_32x32x16_bf16 v[36:51], v[178:181], v[222:225], v[36:51]
	v_mfma_f32_32x32x16_bf16 v[4:19], v[206:209], v[222:225], v[4:19]
	ds_read_b128 v[222:225], v195 offset:41568
	ds_read_b128 v[174:177], v194 offset:4672
	v_mfma_f32_32x32x16_bf16 v[20:35], v[202:205], v[210:213], v[20:35]
	ds_read_b128 v[210:213], v194 offset:4704
	ds_read_b128 v[202:205], v194 offset:64
	v_mfma_f32_32x32x16_bf16 v[52:67], v[178:181], v[214:217], v[52:67]
	ds_read_b128 v[218:221], v195 offset:36960
	ds_read_b128 v[178:181], v195 offset:41536
	v_mfma_f32_32x32x16_bf16 v[20:35], v[206:209], v[214:217], v[20:35]
	ds_read_b128 v[214:217], v195 offset:36928
	ds_read_b128 v[206:209], v194 offset:96
	s_waitcnt lgkmcnt(1)
	v_mfma_f32_32x32x16_bf16 v[52:67], v[202:205], v[214:217], v[52:67]
	s_waitcnt vmcnt(23)
	ds_write_b128 v190, v[132:135] offset:18432
	v_mfma_f32_32x32x16_bf16 v[36:51], v[202:205], v[178:181], v[36:51]
	s_waitcnt vmcnt(22)
	ds_write_b128 v190, v[136:139] offset:55296
	v_mfma_f32_32x32x16_bf16 v[20:35], v[174:177], v[214:217], v[20:35]
	s_waitcnt vmcnt(21)
	ds_write_b128 v191, v[140:143] offset:18432
	v_mfma_f32_32x32x16_bf16 v[4:19], v[174:177], v[178:181], v[4:19]
	s_waitcnt vmcnt(20)
	ds_write_b128 v191, v[198:201] offset:55296
	s_waitcnt lgkmcnt(4)
	v_mfma_f32_32x32x16_bf16 v[52:67], v[206:209], v[218:221], v[52:67]
	s_waitcnt vmcnt(19)
	ds_write_b128 v192, v[226:229] offset:18432
	v_mfma_f32_32x32x16_bf16 v[36:51], v[206:209], v[222:225], v[36:51]
	s_waitcnt vmcnt(18)
	ds_write_b128 v192, v[230:233] offset:55296
	v_mfma_f32_32x32x16_bf16 v[20:35], v[210:213], v[218:221], v[20:35]
	s_waitcnt vmcnt(17)
	ds_write_b128 v193, v[242:245] offset:18432
	v_mfma_f32_32x32x16_bf16 v[4:19], v[210:213], v[222:225], v[4:19]
	s_waitcnt vmcnt(16)
	ds_write_b128 v193, v[246:249] offset:55296
	s_waitcnt lgkmcnt(0)
	s_barrier
; template <class Epi, class ColV>
; DI void gemm_tile(const bf16_t* __restrict__ A, int lda, const bf16_t* __restrict__ Bt, int ldb, int K, int m0, int n0, unsigned char* smem, Epi epi, ColV colv, const bf16_t* __restrict__ HYT = nullptr) {
;     ...
;     auto step = [&](int kt, u32x4 (&ldset)[8], const u32x4 (&stset)[8]) {
;         const int buf = kt & 1;
;         if (kt + 2 < nk) gload(ldset, kt + 2);
;         const bf16_t* Ab = As + (buf * 128 + 64 * wr + li) * LS + 8 * lh;
;         const bf16_t* Bb = Bs + (buf * 128 + 64 * wc + li) * LS + 8 * lh;
;         bf16x8 fa[2][2], fb[2][2], ga[2][2], gb[2][2];
; #pragma unroll
;         for (int k2 = 0; k2 < 2; ++k2) { fa[k2][0] = ld8(Ab + 16 * k2); fa[k2][1] = ld8(Ab + 32 * LS + 16 * k2); fb[k2][0] = ld8(Bb + 16 * k2); fb[k2][1] = ld8(Bb + 32 * LS + 16 * k2); }
;         __builtin_amdgcn_sched_barrier(0);
; #pragma unroll
;         for (int k2 = 0; k2 < 2; ++k2) {
;             acc[0][0] = MFMA(fa[k2][0], fb[k2][0], acc[0][0]); acc[0][1] = MFMA(fa[k2][0], fb[k2][1], acc[0][1]);
;             acc[1][0] = MFMA(fa[k2][1], fb[k2][0], acc[1][0]); acc[1][1] = MFMA(fa[k2][1], fb[k2][1], acc[1][1]);
;         }
; #pragma unroll
;         for (int k2 = 0; k2 < 2; ++k2) { const int ks = 2 + k2; ga[k2][0] = ld8(Ab + 16 * ks); ga[k2][1] = ld8(Ab + 32 * LS + 16 * ks); gb[k2][0] = ld8(Bb + 16 * ks); gb[k2][1] = ld8(Bb + 32 * LS + 16 * ks); }
; #pragma unroll
;         for (int k2 = 0; k2 < 2; ++k2) {
;             acc[0][0] = MFMA(ga[k2][0], gb[k2][0], acc[0][0]); acc[0][1] = MFMA(ga[k2][0], gb[k2][1], acc[0][1]);
;             acc[1][0] = MFMA(ga[k2][1], gb[k2][0], acc[1][0]); acc[1][1] = MFMA(ga[k2][1], gb[k2][1], acc[1][1]);
;         }
;         if (kt + 1 < nk) sstore(stset, buf ^ 1, kt + 1);
; #pragma unroll
;         for (int i = 0; i < 8; ++i) { __builtin_amdgcn_sched_group_barrier(0x008, 1, 0); __builtin_amdgcn_sched_group_barrier(0x100, 1, 0); }
; #pragma unroll
;         for (int i = 0; i < 8; ++i) { __builtin_amdgcn_sched_group_barrier(0x008, 1, 0); __builtin_amdgcn_sched_group_barrier(0x200, 1, 0); }
;         __builtin_amdgcn_sched_barrier(0);
;         __syncthreads();
;     };
;     gload(R0, 0); gload(R1, 1);
;     sstore(R0, 0, 0); __syncthreads();
;     for (int kt = 0; kt < nk; kt += 2) {
;         step(kt, R0, R1);
;         if (kt + 1 < nk) step(kt + 1, R1, R0);
;     }
	global_load_dwordx4 v[132:135], v[164:165], off offset:1024
	global_load_dwordx4 v[136:139], v[162:163], off offset:1024
	global_load_dwordx4 v[140:143], v[160:161], off offset:1024
	global_load_dwordx4 v[198:201], v[158:159], off offset:1024
	global_load_dwordx4 v[226:229], v[156:157], off offset:1024
	global_load_dwordx4 v[230:233], v[154:155], off offset:1024
	global_load_dwordx4 v[242:245], v[152:153], off offset:1024
	global_load_dwordx4 v[246:249], v[146:147], off offset:1024
	ds_read_b128 v[174:177], v196
	ds_read_b128 v[178:181], v196 offset:32
	ds_read_b128 v[202:205], v196 offset:4608
	ds_read_b128 v[206:209], v196 offset:4640
	ds_read_b128 v[210:213], v197 offset:36864
	ds_read_b128 v[214:217], v197 offset:36896
	ds_read_b128 v[218:221], v197 offset:41472
	ds_read_b128 v[222:225], v197 offset:41504
	s_waitcnt lgkmcnt(3)
	v_mfma_f32_32x32x16_bf16 v[52:67], v[174:177], v[210:213], v[52:67]
	s_waitcnt lgkmcnt(1)
	v_mfma_f32_32x32x16_bf16 v[36:51], v[174:177], v[218:221], v[36:51]
	v_mfma_f32_32x32x16_bf16 v[4:19], v[202:205], v[218:221], v[4:19]
	s_waitcnt lgkmcnt(0)
	v_mfma_f32_32x32x16_bf16 v[36:51], v[178:181], v[222:225], v[36:51]
	v_mfma_f32_32x32x16_bf16 v[4:19], v[206:209], v[222:225], v[4:19]
	ds_read_b128 v[222:225], v197 offset:41568
	ds_read_b128 v[174:177], v196 offset:4672
	v_mfma_f32_32x32x16_bf16 v[20:35], v[202:205], v[210:213], v[20:35]
	ds_read_b128 v[210:213], v196 offset:4704
	ds_read_b128 v[202:205], v196 offset:64
	v_mfma_f32_32x32x16_bf16 v[52:67], v[178:181], v[214:217], v[52:67]
	ds_read_b128 v[218:221], v197 offset:36960
	ds_read_b128 v[178:181], v197 offset:41536
	v_mfma_f32_32x32x16_bf16 v[20:35], v[206:209], v[214:217], v[20:35]
	ds_read_b128 v[214:217], v197 offset:36928
	ds_read_b128 v[206:209], v196 offset:96
	s_waitcnt lgkmcnt(1)
	v_mfma_f32_32x32x16_bf16 v[52:67], v[202:205], v[214:217], v[52:67]
	s_waitcnt vmcnt(23)
	ds_write_b128 v190, v[68:71]
	v_mfma_f32_32x32x16_bf16 v[36:51], v[202:205], v[178:181], v[36:51]
	s_waitcnt vmcnt(22)
	ds_write_b128 v190, v[72:75] offset:36864
	v_mfma_f32_32x32x16_bf16 v[20:35], v[174:177], v[214:217], v[20:35]
	s_waitcnt vmcnt(21)
	ds_write_b128 v191, v[76:79]
	v_mfma_f32_32x32x16_bf16 v[4:19], v[174:177], v[178:181], v[4:19]
	s_waitcnt vmcnt(20)
	ds_write_b128 v191, v[80:83] offset:36864
	s_waitcnt lgkmcnt(4)
	v_mfma_f32_32x32x16_bf16 v[52:67], v[206:209], v[218:221], v[52:67]
	s_waitcnt vmcnt(19)
	ds_write_b128 v192, v[84:87]
	v_mfma_f32_32x32x16_bf16 v[36:51], v[206:209], v[222:225], v[36:51]
	s_waitcnt vmcnt(18)
	ds_write_b128 v192, v[92:95] offset:36864
	v_mfma_f32_32x32x16_bf16 v[20:35], v[210:213], v[218:221], v[20:35]
	s_waitcnt vmcnt(17)
	ds_write_b128 v193, v[104:107]
	v_mfma_f32_32x32x16_bf16 v[4:19], v[210:213], v[222:225], v[4:19]
	s_waitcnt vmcnt(16)
	ds_write_b128 v193, v[112:115] offset:36864
	s_waitcnt lgkmcnt(0)
	s_barrier
	v_lshl_add_u64 v[164:165], v[164:165], 0, s[100:101]
	v_lshl_add_u64 v[162:163], v[162:163], 0, s[100:101]
	v_lshl_add_u64 v[160:161], v[160:161], 0, s[100:101]
	v_lshl_add_u64 v[158:159], v[158:159], 0, s[100:101]
	v_lshl_add_u64 v[156:157], v[156:157], 0, s[100:101]
	v_lshl_add_u64 v[154:155], v[154:155], 0, s[100:101]
	v_lshl_add_u64 v[152:153], v[152:153], 0, s[100:101]
	v_lshl_add_u64 v[146:147], v[146:147], 0, s[100:101]
	s_sub_u32 s41, s41, 1
	s_cmp_lg_u32 s41, 0
	s_cbranch_scc1 .Lg3_phase11
	global_load_dwordx4 v[68:71], v[164:165], off offset:384
	global_load_dwordx4 v[72:75], v[162:163], off offset:384
	global_load_dwordx4 v[76:79], v[160:161], off offset:384
	global_load_dwordx4 v[80:83], v[158:159], off offset:384
	global_load_dwordx4 v[84:87], v[156:157], off offset:384
	global_load_dwordx4 v[92:95], v[154:155], off offset:384
	global_load_dwordx4 v[104:107], v[152:153], off offset:384
	global_load_dwordx4 v[112:115], v[146:147], off offset:384
	ds_read_b128 v[174:177], v194
	ds_read_b128 v[178:181], v194 offset:32
	ds_read_b128 v[202:205], v194 offset:4608
	ds_read_b128 v[206:209], v194 offset:4640
	ds_read_b128 v[210:213], v195 offset:36864
	ds_read_b128 v[214:217], v195 offset:36896
	ds_read_b128 v[218:221], v195 offset:41472
	ds_read_b128 v[222:225], v195 offset:41504
	s_waitcnt lgkmcnt(3)
	v_mfma_f32_32x32x16_bf16 v[52:67], v[174:177], v[210:213], v[52:67]
	s_waitcnt lgkmcnt(1)
	v_mfma_f32_32x32x16_bf16 v[36:51], v[174:177], v[218:221], v[36:51]
	v_mfma_f32_32x32x16_bf16 v[4:19], v[202:205], v[218:221], v[4:19]
	s_waitcnt lgkmcnt(0)
	v_mfma_f32_32x32x16_bf16 v[36:51], v[178:181], v[222:225], v[36:51]
	v_mfma_f32_32x32x16_bf16 v[4:19], v[206:209], v[222:225], v[4:19]
	ds_read_b128 v[222:225], v195 offset:41568
	ds_read_b128 v[174:177], v194 offset:4672
	v_mfma_f32_32x32x16_bf16 v[20:35], v[202:205], v[210:213], v[20:35]
	ds_read_b128 v[210:213], v194 offset:4704
	ds_read_b128 v[202:205], v194 offset:64
	v_mfma_f32_32x32x16_bf16 v[52:67], v[178:181], v[214:217], v[52:67]
	ds_read_b128 v[218:221], v195 offset:36960
	ds_read_b128 v[178:181], v195 offset:41536
	v_mfma_f32_32x32x16_bf16 v[20:35], v[206:209], v[214:217], v[20:35]
	ds_read_b128 v[214:217], v195 offset:36928
	ds_read_b128 v[206:209], v194 offset:96
	s_waitcnt lgkmcnt(1)
	v_mfma_f32_32x32x16_bf16 v[52:67], v[202:205], v[214:217], v[52:67]
	s_waitcnt vmcnt(23)
	ds_write_b128 v190, v[88:91] offset:18432
	v_mfma_f32_32x32x16_bf16 v[36:51], v[202:205], v[178:181], v[36:51]
	s_waitcnt vmcnt(22)
	ds_write_b128 v190, v[96:99] offset:55296
	v_mfma_f32_32x32x16_bf16 v[20:35], v[174:177], v[214:217], v[20:35]
	s_waitcnt vmcnt(21)
	ds_write_b128 v191, v[100:103] offset:18432
	v_mfma_f32_32x32x16_bf16 v[4:19], v[174:177], v[178:181], v[4:19]
	s_waitcnt vmcnt(20)
	ds_write_b128 v191, v[108:111] offset:55296
	s_waitcnt lgkmcnt(4)
	v_mfma_f32_32x32x16_bf16 v[52:67], v[206:209], v[218:221], v[52:67]
	s_waitcnt vmcnt(19)
	ds_write_b128 v192, v[116:119] offset:18432
	v_mfma_f32_32x32x16_bf16 v[36:51], v[206:209], v[222:225], v[36:51]
	s_waitcnt vmcnt(18)
	ds_write_b128 v192, v[120:123] offset:55296
	v_mfma_f32_32x32x16_bf16 v[20:35], v[210:213], v[218:221], v[20:35]
	s_waitcnt vmcnt(17)
	ds_write_b128 v193, v[124:127] offset:18432
	v_mfma_f32_32x32x16_bf16 v[4:19], v[210:213], v[222:225], v[4:19]
	s_waitcnt vmcnt(16)
	ds_write_b128 v193, v[128:131] offset:55296
	s_waitcnt lgkmcnt(0)
	s_barrier
; template <class Epi, class ColV>
; DI void gemm_tile(const bf16_t* __restrict__ A, int lda, const bf16_t* __restrict__ Bt, int ldb, int K, int m0, int n0, unsigned char* smem, Epi epi, ColV colv, const bf16_t* __restrict__ HYT = nullptr) {
;     ...
;     auto step = [&](int kt, u32x4 (&ldset)[8], const u32x4 (&stset)[8]) {
;         const int buf = kt & 1;
;         if (kt + 2 < nk) gload(ldset, kt + 2);
;         const bf16_t* Ab = As + (buf * 128 + 64 * wr + li) * LS + 8 * lh;
;         const bf16_t* Bb = Bs + (buf * 128 + 64 * wc + li) * LS + 8 * lh;
;         bf16x8 fa[2][2], fb[2][2], ga[2][2], gb[2][2];
; #pragma unroll
;         for (int k2 = 0; k2 < 2; ++k2) { fa[k2][0] = ld8(Ab + 16 * k2); fa[k2][1] = ld8(Ab + 32 * LS + 16 * k2); fb[k2][0] = ld8(Bb + 16 * k2); fb[k2][1] = ld8(Bb + 32 * LS + 16 * k2); }
;         __builtin_amdgcn_sched_barrier(0);
; #pragma unroll
;         for (int k2 = 0; k2 < 2; ++k2) {
;             acc[0][0] = MFMA(fa[k2][0], fb[k2][0], acc[0][0]); acc[0][1] = MFMA(fa[k2][0], fb[k2][1], acc[0][1]);
;             acc[1][0] = MFMA(fa[k2][1], fb[k2][0], acc[1][0]); acc[1][1] = MFMA(fa[k2][1], fb[k2][1], acc[1][1]);
;         }
; #pragma unroll
;         for (int k2 = 0; k2 < 2; ++k2) { const int ks = 2 + k2; ga[k2][0] = ld8(Ab + 16 * ks); ga[k2][1] = ld8(Ab + 32 * LS + 16 * ks); gb[k2][0] = ld8(Bb + 16 * ks); gb[k2][1] = ld8(Bb + 32 * LS + 16 * ks); }
; #pragma unroll
;         for (int k2 = 0; k2 < 2; ++k2) {
;             acc[0][0] = MFMA(ga[k2][0], gb[k2][0], acc[0][0]); acc[0][1] = MFMA(ga[k2][0], gb[k2][1], acc[0][1]);
;             acc[1][0] = MFMA(ga[k2][1], gb[k2][0], acc[1][0]); acc[1][1] = MFMA(ga[k2][1], gb[k2][1], acc[1][1]);
;         }
;         if (kt + 1 < nk) sstore(stset, buf ^ 1, kt + 1);
; #pragma unroll
;         for (int i = 0; i < 8; ++i) { __builtin_amdgcn_sched_group_barrier(0x008, 1, 0); __builtin_amdgcn_sched_group_barrier(0x100, 1, 0); }
; #pragma unroll
;         for (int i = 0; i < 8; ++i) { __builtin_amdgcn_sched_group_barrier(0x008, 1, 0); __builtin_amdgcn_sched_group_barrier(0x200, 1, 0); }
;         __builtin_amdgcn_sched_barrier(0);
;         __syncthreads();
;     };
;     gload(R0, 0); gload(R1, 1);
;     sstore(R0, 0, 0); __syncthreads();
;     for (int kt = 0; kt < nk; kt += 2) {
;         step(kt, R0, R1);
;         if (kt + 1 < nk) step(kt + 1, R1, R0);
	ds_read_b128 v[174:177], v196
	ds_read_b128 v[178:181], v196 offset:32
	ds_read_b128 v[202:205], v196 offset:4608
	ds_read_b128 v[206:209], v196 offset:4640
	ds_read_b128 v[210:213], v197 offset:36864
	ds_read_b128 v[214:217], v197 offset:36896
	ds_read_b128 v[218:221], v197 offset:41472
	ds_read_b128 v[222:225], v197 offset:41504
	s_waitcnt lgkmcnt(3)
	v_mfma_f32_32x32x16_bf16 v[52:67], v[174:177], v[210:213], v[52:67]
	s_waitcnt lgkmcnt(1)
	v_mfma_f32_32x32x16_bf16 v[36:51], v[174:177], v[218:221], v[36:51]
	v_mfma_f32_32x32x16_bf16 v[4:19], v[202:205], v[218:221], v[4:19]
	s_waitcnt lgkmcnt(0)
	v_mfma_f32_32x32x16_bf16 v[36:51], v[178:181], v[222:225], v[36:51]
	v_mfma_f32_32x32x16_bf16 v[4:19], v[206:209], v[222:225], v[4:19]
	ds_read_b128 v[222:225], v197 offset:41568
	ds_read_b128 v[174:177], v196 offset:4672
	v_mfma_f32_32x32x16_bf16 v[20:35], v[202:205], v[210:213], v[20:35]
	ds_read_b128 v[210:213], v196 offset:4704
	ds_read_b128 v[202:205], v196 offset:64
	v_mfma_f32_32x32x16_bf16 v[52:67], v[178:181], v[214:217], v[52:67]
	ds_read_b128 v[218:221], v197 offset:36960
	ds_read_b128 v[178:181], v197 offset:41536
	v_mfma_f32_32x32x16_bf16 v[20:35], v[206:209], v[214:217], v[20:35]
	ds_read_b128 v[214:217], v197 offset:36928
	ds_read_b128 v[206:209], v196 offset:96
	s_waitcnt lgkmcnt(1)
	v_mfma_f32_32x32x16_bf16 v[52:67], v[202:205], v[214:217], v[52:67]
	s_waitcnt vmcnt(15)
	ds_write_b128 v190, v[132:135]
	v_mfma_f32_32x32x16_bf16 v[36:51], v[202:205], v[178:181], v[36:51]
	s_waitcnt vmcnt(14)
	ds_write_b128 v190, v[136:139] offset:36864
	v_mfma_f32_32x32x16_bf16 v[20:35], v[174:177], v[214:217], v[20:35]
	s_waitcnt vmcnt(13)
	ds_write_b128 v191, v[140:143]
	v_mfma_f32_32x32x16_bf16 v[4:19], v[174:177], v[178:181], v[4:19]
	s_waitcnt vmcnt(12)
	ds_write_b128 v191, v[198:201] offset:36864
	s_waitcnt lgkmcnt(4)
	v_mfma_f32_32x32x16_bf16 v[52:67], v[206:209], v[218:221], v[52:67]
	s_waitcnt vmcnt(11)
	ds_write_b128 v192, v[226:229]
	v_mfma_f32_32x32x16_bf16 v[36:51], v[206:209], v[222:225], v[36:51]
	s_waitcnt vmcnt(10)
	ds_write_b128 v192, v[230:233] offset:36864
	v_mfma_f32_32x32x16_bf16 v[20:35], v[210:213], v[218:221], v[20:35]
	s_waitcnt vmcnt(9)
	ds_write_b128 v193, v[242:245]
	v_mfma_f32_32x32x16_bf16 v[4:19], v[210:213], v[222:225], v[4:19]
	s_waitcnt vmcnt(8)
	ds_write_b128 v193, v[246:249] offset:36864
	s_waitcnt lgkmcnt(0)
	s_barrier
	ds_read_b128 v[174:177], v194
	ds_read_b128 v[178:181], v194 offset:32
	ds_read_b128 v[202:205], v194 offset:4608
	ds_read_b128 v[206:209], v194 offset:4640
	ds_read_b128 v[210:213], v195 offset:36864
	ds_read_b128 v[214:217], v195 offset:36896
	ds_read_b128 v[218:221], v195 offset:41472
	ds_read_b128 v[222:225], v195 offset:41504
	s_waitcnt lgkmcnt(3)
	v_mfma_f32_32x32x16_bf16 v[52:67], v[174:177], v[210:213], v[52:67]
	s_waitcnt lgkmcnt(1)
	v_mfma_f32_32x32x16_bf16 v[36:51], v[174:177], v[218:221], v[36:51]
	v_mfma_f32_32x32x16_bf16 v[4:19], v[202:205], v[218:221], v[4:19]
	s_waitcnt lgkmcnt(0)
	v_mfma_f32_32x32x16_bf16 v[36:51], v[178:181], v[222:225], v[36:51]
	v_mfma_f32_32x32x16_bf16 v[4:19], v[206:209], v[222:225], v[4:19]
	ds_read_b128 v[222:225], v195 offset:41568
	ds_read_b128 v[174:177], v194 offset:4672
	v_mfma_f32_32x32x16_bf16 v[20:35], v[202:205], v[210:213], v[20:35]
	ds_read_b128 v[210:213], v194 offset:4704
	ds_read_b128 v[202:205], v194 offset:64
	v_mfma_f32_32x32x16_bf16 v[52:67], v[178:181], v[214:217], v[52:67]
	ds_read_b128 v[218:221], v195 offset:36960
	ds_read_b128 v[178:181], v195 offset:41536
	v_mfma_f32_32x32x16_bf16 v[20:35], v[206:209], v[214:217], v[20:35]
	ds_read_b128 v[214:217], v195 offset:36928
	ds_read_b128 v[206:209], v194 offset:96
	s_waitcnt lgkmcnt(1)
	v_mfma_f32_32x32x16_bf16 v[52:67], v[202:205], v[214:217], v[52:67]
	s_waitcnt vmcnt(7)
	ds_write_b128 v190, v[68:71] offset:18432
	v_mfma_f32_32x32x16_bf16 v[36:51], v[202:205], v[178:181], v[36:51]
	s_waitcnt vmcnt(6)
	ds_write_b128 v190, v[72:75] offset:55296
	v_mfma_f32_32x32x16_bf16 v[20:35], v[174:177], v[214:217], v[20:35]
	s_waitcnt vmcnt(5)
	ds_write_b128 v191, v[76:79] offset:18432
	v_mfma_f32_32x32x16_bf16 v[4:19], v[174:177], v[178:181], v[4:19]
	s_waitcnt vmcnt(4)
	ds_write_b128 v191, v[80:83] offset:55296
	s_waitcnt lgkmcnt(4)
	v_mfma_f32_32x32x16_bf16 v[52:67], v[206:209], v[218:221], v[52:67]
	s_waitcnt vmcnt(3)
	ds_write_b128 v192, v[84:87] offset:18432
	v_mfma_f32_32x32x16_bf16 v[36:51], v[206:209], v[222:225], v[36:51]
	s_waitcnt vmcnt(2)
	ds_write_b128 v192, v[92:95] offset:55296
	v_mfma_f32_32x32x16_bf16 v[20:35], v[210:213], v[218:221], v[20:35]
	s_waitcnt vmcnt(1)
	ds_write_b128 v193, v[104:107] offset:18432
	v_mfma_f32_32x32x16_bf16 v[4:19], v[210:213], v[222:225], v[4:19]
	s_waitcnt vmcnt(0)
	ds_write_b128 v193, v[112:115] offset:55296
	s_waitcnt lgkmcnt(0)
	s_barrier
	ds_read_b128 v[174:177], v196
	ds_read_b128 v[178:181], v196 offset:32
	ds_read_b128 v[202:205], v196 offset:4608
	ds_read_b128 v[206:209], v196 offset:4640
	ds_read_b128 v[210:213], v197 offset:36864
	ds_read_b128 v[214:217], v197 offset:36896
	ds_read_b128 v[218:221], v197 offset:41472
	ds_read_b128 v[222:225], v197 offset:41504
	s_waitcnt lgkmcnt(3)
	v_mfma_f32_32x32x16_bf16 v[52:67], v[174:177], v[210:213], v[52:67]
	s_waitcnt lgkmcnt(1)
	v_mfma_f32_32x32x16_bf16 v[36:51], v[174:177], v[218:221], v[36:51]
	v_mfma_f32_32x32x16_bf16 v[4:19], v[202:205], v[218:221], v[4:19]
	s_waitcnt lgkmcnt(0)
	v_mfma_f32_32x32x16_bf16 v[36:51], v[178:181], v[222:225], v[36:51]
	v_mfma_f32_32x32x16_bf16 v[4:19], v[206:209], v[222:225], v[4:19]
	ds_read_b128 v[222:225], v197 offset:41568
	ds_read_b128 v[174:177], v196 offset:4672
	v_mfma_f32_32x32x16_bf16 v[20:35], v[202:205], v[210:213], v[20:35]
	ds_read_b128 v[210:213], v196 offset:4704
	ds_read_b128 v[202:205], v196 offset:64
	v_mfma_f32_32x32x16_bf16 v[52:67], v[178:181], v[214:217], v[52:67]
	ds_read_b128 v[218:221], v197 offset:36960
	ds_read_b128 v[178:181], v197 offset:41536
	v_mfma_f32_32x32x16_bf16 v[20:35], v[206:209], v[214:217], v[20:35]
	ds_read_b128 v[214:217], v197 offset:36928
	ds_read_b128 v[206:209], v196 offset:96
	s_waitcnt lgkmcnt(1)
	v_mfma_f32_32x32x16_bf16 v[52:67], v[202:205], v[214:217], v[52:67]
	v_mfma_f32_32x32x16_bf16 v[36:51], v[202:205], v[178:181], v[36:51]
	v_mfma_f32_32x32x16_bf16 v[20:35], v[174:177], v[214:217], v[20:35]
	v_mfma_f32_32x32x16_bf16 v[4:19], v[174:177], v[178:181], v[4:19]
	s_waitcnt lgkmcnt(0)
	v_mfma_f32_32x32x16_bf16 v[52:67], v[206:209], v[218:221], v[52:67]
	v_mfma_f32_32x32x16_bf16 v[36:51], v[206:209], v[222:225], v[36:51]
	v_mfma_f32_32x32x16_bf16 v[20:35], v[210:213], v[218:221], v[20:35]
	v_mfma_f32_32x32x16_bf16 v[4:19], v[210:213], v[222:225], v[4:19]
	s_waitcnt lgkmcnt(0)
	s_barrier
	s_nop 7
	s_nop 3
	s_branch .LBB0_37
